# dilated units: K fragments of QK^T double-buffered through a spare register pair (reads of slice d+1 in flight under slice d's MFMAs)
# baseline (speedup 1.0000x reference)
.LBB0_506:
	v_sub_u32_e32 v228, v184, v169
	v_subrev_u32_e32 v208, s92, v228
	v_cvt_f32_i32_e32 v16, v208
	s_andn2_b64 vcc, exec, s[96:97]
	v_add_f32_e32 v14, -1.0, v16
	v_pk_add_f32 v[0:1], v[16:17], s[12:13] op_sel_hi:[0,1]
	v_pk_add_f32 v[2:3], v[16:17], s[24:25] op_sel_hi:[0,1]
	v_pk_add_f32 v[4:5], v[16:17], s[28:29] op_sel_hi:[0,1]
	v_pk_add_f32 v[6:7], v[16:17], s[30:31] op_sel_hi:[0,1]
	v_pk_add_f32 v[8:9], v[16:17], s[36:37] op_sel_hi:[0,1]
	v_pk_add_f32 v[10:11], v[16:17], s[38:39] op_sel_hi:[0,1]
	v_pk_add_f32 v[12:13], v[16:17], s[40:41] op_sel_hi:[0,1]
	v_and_b32_e32 v1, 0x7fffffff, v1
	v_and_b32_e32 v0, 0x7fffffff, v0
	v_and_b32_e32 v3, 0x7fffffff, v3
	v_and_b32_e32 v2, 0x7fffffff, v2
	v_and_b32_e32 v5, 0x7fffffff, v5
	v_and_b32_e32 v4, 0x7fffffff, v4
	v_and_b32_e32 v7, 0x7fffffff, v7
	v_and_b32_e32 v6, 0x7fffffff, v6
	v_and_b32_e32 v9, 0x7fffffff, v9
	v_and_b32_e32 v8, 0x7fffffff, v8
	v_and_b32_e32 v11, 0x7fffffff, v11
	v_and_b32_e32 v10, 0x7fffffff, v10
	v_and_b32_e32 v13, 0x7fffffff, v13
	v_and_b32_e32 v12, 0x7fffffff, v12
	v_and_b32_e32 v18, 0x7fffffff, v16
	v_and_b32_e32 v19, 0x7fffffff, v14
	v_pk_mul_f32 v[14:15], v[12:13], v[186:187] op_sel_hi:[1,0] neg_lo:[0,1] neg_hi:[0,1]
	v_pk_mul_f32 v[12:13], v[10:11], v[186:187] op_sel_hi:[1,0] neg_lo:[0,1] neg_hi:[0,1]
	v_pk_mul_f32 v[10:11], v[8:9], v[186:187] op_sel_hi:[1,0] neg_lo:[0,1] neg_hi:[0,1]
	v_pk_mul_f32 v[8:9], v[6:7], v[186:187] op_sel_hi:[1,0] neg_lo:[0,1] neg_hi:[0,1]
	v_pk_mul_f32 v[6:7], v[4:5], v[186:187] op_sel_hi:[1,0] neg_lo:[0,1] neg_hi:[0,1]
	v_pk_mul_f32 v[4:5], v[2:3], v[186:187] op_sel_hi:[1,0] neg_lo:[0,1] neg_hi:[0,1]
	v_pk_mul_f32 v[2:3], v[0:1], v[186:187] op_sel_hi:[1,0] neg_lo:[0,1] neg_hi:[0,1]
	v_pk_mul_f32 v[0:1], v[18:19], v[186:187] op_sel_hi:[1,0] neg_lo:[0,1] neg_hi:[0,1]
	v_pk_add_f32 v[18:19], v[16:17], s[64:65] op_sel_hi:[0,1]
	v_pk_add_f32 v[20:21], v[16:17], s[66:67] op_sel_hi:[0,1]
	v_pk_add_f32 v[22:23], v[16:17], s[68:69] op_sel_hi:[0,1]
	v_pk_add_f32 v[26:27], v[16:17], s[72:73] op_sel_hi:[0,1]
	v_pk_add_f32 v[28:29], v[16:17], s[74:75] op_sel_hi:[0,1]
	v_pk_add_f32 v[30:31], v[16:17], s[76:77] op_sel_hi:[0,1]
	v_and_b32_e32 v145, 0x7fffffff, v31
	v_and_b32_e32 v144, 0x7fffffff, v30
	v_and_b32_e32 v147, 0x7fffffff, v29
	v_and_b32_e32 v146, 0x7fffffff, v28
	v_and_b32_e32 v149, 0x7fffffff, v27
	v_and_b32_e32 v148, 0x7fffffff, v26
	v_and_b32_e32 v23, 0x7fffffff, v23
	v_and_b32_e32 v22, 0x7fffffff, v22
	v_and_b32_e32 v21, 0x7fffffff, v21
	v_and_b32_e32 v20, 0x7fffffff, v20
	v_and_b32_e32 v19, 0x7fffffff, v19
	v_and_b32_e32 v18, 0x7fffffff, v18
	v_pk_mul_f32 v[30:31], v[18:19], v[186:187] op_sel_hi:[1,0] neg_lo:[0,1] neg_hi:[0,1]
	v_pk_mul_f32 v[28:29], v[20:21], v[186:187] op_sel_hi:[1,0] neg_lo:[0,1] neg_hi:[0,1]
	v_pk_mul_f32 v[26:27], v[22:23], v[186:187] op_sel_hi:[1,0] neg_lo:[0,1] neg_hi:[0,1]
	v_pk_mul_f32 v[22:23], v[148:149], v[186:187] op_sel_hi:[1,0] neg_lo:[0,1] neg_hi:[0,1]
	v_pk_mul_f32 v[20:21], v[146:147], v[186:187] op_sel_hi:[1,0] neg_lo:[0,1] neg_hi:[0,1]
	v_pk_mul_f32 v[18:19], v[144:145], v[186:187] op_sel_hi:[1,0] neg_lo:[0,1] neg_hi:[0,1]
	ds_read_b128 v[144:147], v223
	ds_read_b128 v[148:151], v223 offset:4096
	ds_read_b128 v[238:241], v224
	ds_read_b128 v[242:245], v224 offset:4096
	v_pk_add_f32 v[24:25], v[16:17], s[70:71] op_sel_hi:[0,1]
	v_pk_add_f32 v[16:17], v[16:17], s[78:79] op_sel_hi:[0,1]
	v_and_b32_e32 v17, 0x7fffffff, v17
	v_and_b32_e32 v16, 0x7fffffff, v16
	v_and_b32_e32 v25, 0x7fffffff, v25
	v_and_b32_e32 v24, 0x7fffffff, v24
	v_pk_mul_f32 v[24:25], v[24:25], v[186:187] op_sel_hi:[1,0] neg_lo:[0,1] neg_hi:[0,1]
	v_pk_mul_f32 v[16:17], v[16:17], v[186:187] op_sel_hi:[1,0] neg_lo:[0,1] neg_hi:[0,1]
	s_waitcnt vmcnt(3) lgkmcnt(3)
	v_mfma_f32_32x32x16_bf16 v[0:15], v[144:147], v[136:139], v[0:15]
	s_waitcnt lgkmcnt(2)
	v_mfma_f32_32x32x16_bf16 v[16:31], v[148:151], v[136:139], v[16:31]
	ds_read_b128 v[144:147], v225
	ds_read_b128 v[148:151], v225 offset:4096
	s_waitcnt vmcnt(2) lgkmcnt(3)
	v_mfma_f32_32x32x16_bf16 v[0:15], v[238:241], v[132:135], v[0:15]
	s_waitcnt lgkmcnt(2)
	v_mfma_f32_32x32x16_bf16 v[16:31], v[242:245], v[132:135], v[16:31]
	ds_read_b128 v[238:241], v226
	ds_read_b128 v[242:245], v226 offset:4096
	s_waitcnt vmcnt(1) lgkmcnt(3)
	v_mfma_f32_32x32x16_bf16 v[0:15], v[144:147], v[128:131], v[0:15]
	s_waitcnt lgkmcnt(2)
	v_mfma_f32_32x32x16_bf16 v[16:31], v[148:151], v[128:131], v[16:31]
	s_waitcnt vmcnt(0) lgkmcnt(1)
	v_mfma_f32_32x32x16_bf16 v[0:15], v[238:241], v[124:127], v[0:15]
	s_waitcnt lgkmcnt(0)
	v_mfma_f32_32x32x16_bf16 v[16:31], v[242:245], v[124:127], v[16:31]
	s_nop 9
	v_max_f32_e32 v144, v1, v17
	v_max_f32_e32 v145, v2, v18
	v_max3_f32 v144, v0, v16, v144
	v_max_f32_e32 v146, v3, v19
	v_max3_f32 v144, v144, v145, v146
	v_max_f32_e32 v145, v4, v20
	v_max_f32_e32 v146, v5, v21
	v_max3_f32 v144, v144, v145, v146
	v_max_f32_e32 v145, v6, v22
	v_max_f32_e32 v146, v7, v23
	v_max3_f32 v144, v144, v145, v146
	v_max_f32_e32 v145, v8, v24
	v_max_f32_e32 v146, v9, v25
	v_max3_f32 v144, v144, v145, v146
	v_max_f32_e32 v145, v10, v26
	v_max_f32_e32 v146, v11, v27
	v_max3_f32 v144, v144, v145, v146
	v_max_f32_e32 v145, v12, v28
	v_max_f32_e32 v146, v13, v29
	v_max3_f32 v144, v144, v145, v146
	v_max_f32_e32 v145, v14, v30
	v_max_f32_e32 v146, v15, v31
	v_max3_f32 v144, v144, v145, v146
	v_mov_b32_e32 v145, v144
	s_nop 1
	v_permlane32_swap_b32 v144, v145
	s_nop 1
	ds_read_b128 v[234:237], v224 offset:8192
	v_max_f32_e32 v145, v145, v145
	v_max_f32_e32 v144, v144, v144
	v_max_f32_e32 v188, v144, v145
	v_sub_f32_e32 v0, v0, v188
	v_sub_f32_e32 v16, v16, v188
	v_sub_f32_e32 v1, v1, v188
	v_sub_f32_e32 v17, v17, v188
	v_exp_f32_e32 v184, v0
	v_exp_f32_e32 v185, v16
	v_sub_f32_e32 v2, v2, v188
	v_sub_f32_e32 v18, v18, v188
	v_exp_f32_e32 v190, v1
	v_exp_f32_e32 v191, v17
	v_sub_f32_e32 v3, v3, v188
	v_sub_f32_e32 v19, v19, v188
	v_exp_f32_e32 v192, v2
	v_exp_f32_e32 v193, v18
	v_sub_f32_e32 v4, v4, v188
	v_sub_f32_e32 v20, v20, v188
	v_exp_f32_e32 v194, v3
	v_exp_f32_e32 v195, v19
	v_sub_f32_e32 v5, v5, v188
	v_sub_f32_e32 v21, v21, v188
	v_pk_add_f32 v[0:1], v[184:185], 0 op_sel_hi:[1,0]
	v_exp_f32_e32 v196, v4
	v_exp_f32_e32 v197, v20
	v_sub_f32_e32 v6, v6, v188
	v_sub_f32_e32 v22, v22, v188
	v_pk_add_f32 v[0:1], v[190:191], v[0:1]
	v_exp_f32_e32 v198, v5
	v_exp_f32_e32 v199, v21
	v_sub_f32_e32 v7, v7, v188
	v_sub_f32_e32 v23, v23, v188
	v_pk_add_f32 v[0:1], v[192:193], v[0:1]
	v_exp_f32_e32 v204, v6
	v_exp_f32_e32 v205, v22
	v_sub_f32_e32 v8, v8, v188
	v_sub_f32_e32 v24, v24, v188
	v_pk_add_f32 v[0:1], v[194:195], v[0:1]
	v_exp_f32_e32 v206, v7
	v_exp_f32_e32 v207, v23
	v_sub_f32_e32 v9, v9, v188
	v_sub_f32_e32 v25, v25, v188
	v_exp_f32_e32 v144, v8
	v_exp_f32_e32 v145, v24
	v_pk_add_f32 v[0:1], v[196:197], v[0:1]
	v_sub_f32_e32 v10, v10, v188
	v_sub_f32_e32 v26, v26, v188
	v_exp_f32_e32 v146, v9
	v_exp_f32_e32 v147, v25
	v_pk_add_f32 v[0:1], v[198:199], v[0:1]
	v_sub_f32_e32 v11, v11, v188
	v_sub_f32_e32 v27, v27, v188
	v_exp_f32_e32 v148, v10
	v_exp_f32_e32 v149, v26
	v_pk_add_f32 v[0:1], v[204:205], v[0:1]
	v_sub_f32_e32 v12, v12, v188
	v_sub_f32_e32 v28, v28, v188
	v_exp_f32_e32 v150, v11
	v_exp_f32_e32 v151, v27
	v_pk_add_f32 v[0:1], v[206:207], v[0:1]
	v_sub_f32_e32 v13, v13, v188
	v_sub_f32_e32 v29, v29, v188
	v_exp_f32_e32 v152, v12
	v_exp_f32_e32 v153, v28
	v_pk_add_f32 v[0:1], v[144:145], v[0:1]
	v_sub_f32_e32 v14, v14, v188
	v_sub_f32_e32 v30, v30, v188
	v_exp_f32_e32 v154, v13
	v_exp_f32_e32 v155, v29
	v_pk_add_f32 v[0:1], v[146:147], v[0:1]
	ds_read_b128 v[4:7], v223 offset:8192
	v_sub_f32_e32 v15, v15, v188
	v_sub_f32_e32 v31, v31, v188
	v_exp_f32_e32 v156, v14
	v_exp_f32_e32 v157, v30
	v_pk_add_f32 v[0:1], v[148:149], v[0:1]
	v_exp_f32_e32 v158, v15
	v_exp_f32_e32 v159, v31
	v_pk_add_f32 v[0:1], v[150:151], v[0:1]
	v_cvt_pk_bf16_f32 v2, v196, v198
	v_pk_add_f32 v[0:1], v[152:153], v[0:1]
	v_cvt_pk_bf16_f32 v3, v204, v206
	v_pk_add_f32 v[0:1], v[154:155], v[0:1]
	v_cvt_pk_bf16_f32 v230, v144, v146
	v_pk_add_f32 v[0:1], v[156:157], v[0:1]
	v_cvt_pk_bf16_f32 v231, v148, v150
	v_pk_add_f32 v[0:1], v[158:159], v[0:1]
	v_cvt_pk_bf16_f32 v232, v152, v154
	v_pk_add_f32 v[0:1], v[0:1], v[0:1] op_sel_hi:[0,1]
	v_mov_b32_e32 v189, v1
	v_cvt_pk_bf16_f32 v0, v184, v190
	v_cvt_pk_bf16_f32 v1, v192, v194
	v_cvt_pk_bf16_f32 v233, v156, v158
	v_cvt_pk_bf16_f32 v190, v185, v191
	s_waitcnt lgkmcnt(0)
	v_mfma_f32_32x32x16_bf16 v[16:31], v[4:7], v[0:3], 0
	ds_read_b128 v[4:7], v223 offset:12288
	v_cvt_pk_bf16_f32 v191, v193, v195
	v_cvt_pk_bf16_f32 v192, v197, v199
	ds_read_b128 v[194:197], v225 offset:8192
	v_cvt_pk_bf16_f32 v193, v205, v207
	v_cvt_pk_bf16_f32 v144, v145, v147
	v_cvt_pk_bf16_f32 v145, v149, v151
	v_mfma_f32_32x32x16_bf16 v[16:31], v[234:237], v[230:233], v[16:31]
	ds_read_b128 v[234:237], v224 offset:12288
	ds_read_b128 v[148:151], v226 offset:8192
	v_cvt_pk_bf16_f32 v146, v153, v155
	v_cvt_pk_bf16_f32 v147, v157, v159
	v_add_f32_e64 v188, v188, 0
	v_add_f32_e64 v189, v189, 0
	s_waitcnt lgkmcnt(3)
	v_mfma_f32_32x32x16_bf16 v[0:15], v[4:7], v[0:3], 0
	s_waitcnt lgkmcnt(2)
	v_mfma_f32_32x32x16_bf16 v[16:31], v[194:197], v[190:193], v[16:31]
	ds_read_b128 v[194:197], v225 offset:12288
	s_waitcnt lgkmcnt(2)
	v_mfma_f32_32x32x16_bf16 v[0:15], v[234:237], v[230:233], v[0:15]
	s_waitcnt lgkmcnt(1)
	v_mfma_f32_32x32x16_bf16 v[16:31], v[148:151], v[144:147], v[16:31]
	ds_read_b128 v[148:151], v226 offset:12288
	s_waitcnt lgkmcnt(1)
	v_mfma_f32_32x32x16_bf16 v[0:15], v[194:197], v[190:193], v[0:15]
	s_waitcnt lgkmcnt(0)
	v_mfma_f32_32x32x16_bf16 v[0:15], v[148:151], v[144:147], v[0:15]
	s_cbranch_vccnz .LBB0_511
	s_and_b64 vcc, exec, s[90:91]
	ds_write_b128 v222, v[64:67]
	ds_write_b128 v222, v[68:71] offset:8192
	ds_write_b128 v222, v[72:75] offset:1024
	ds_write_b128 v222, v[76:79] offset:9216
	ds_write_b128 v222, v[80:83] offset:2048
	ds_write_b128 v222, v[84:87] offset:10240
	ds_write_b128 v222, v[88:91] offset:3072
	ds_write_b128 v222, v[92:95] offset:11264
	ds_write_b128 v222, v[96:99] offset:4096
	ds_write_b128 v222, v[100:103] offset:12288
	ds_write_b128 v222, v[104:107] offset:5120
	ds_write_b128 v222, v[108:111] offset:13312
	ds_write_b128 v222, v[112:115] offset:6144
	ds_write_b128 v222, v[116:119] offset:14336
	ds_write_b128 v222, v[120:123] offset:7168
	ds_write_b128 v222, v[140:143] offset:15360
	s_cbranch_vccz .LBB0_512
	v_mov_b64_e32 v[158:159], v[34:35]
	v_mov_b64_e32 v[154:155], v[38:39]
	v_mov_b64_e32 v[150:151], v[42:43]
	v_mov_b64_e32 v[146:147], v[46:47]
	s_andn2_b64 vcc, exec, s[86:87]
	v_mov_b64_e32 v[192:193], v[60:61]
	v_mov_b64_e32 v[194:195], v[62:63]
	v_mov_b64_e32 v[196:197], v[200:201]
	v_mov_b64_e32 v[198:199], v[202:203]
	v_mov_b64_e32 v[190:191], v[56:57]
	v_mov_b32_e32 v177, v59
	s_mov_b32 s90, s94
	s_mov_b32 s95, s15
	s_mov_b32 s34, s48
	v_mov_b32_e32 v184, v58
	s_mov_b32 s93, s35
	s_mov_b32 s56, s33
	v_mov_b64_e32 v[156:157], v[32:33]
	v_mov_b64_e32 v[152:153], v[36:37]
	v_mov_b64_e32 v[148:149], v[40:41]
	v_mov_b64_e32 v[144:145], v[44:45]
	s_cbranch_vccnz .LBB0_510
	s_add_i32 s8, s14, s63
	s_lshr_b32 s56, s8, 8
	s_mul_hi_u32 s85, s56, 0x55555556
	s_mul_i32 s85, s85, 3
	s_sub_i32 s93, s56, s85
	s_lshl_b32 s95, s93, 1
	s_lshr_b32 s90, 0x100, s95
	s_and_b32 s34, s8, 0xff
	s_sub_i32 s85, 8, s95
	s_add_i32 s90, s90, -1
	s_mul_hi_u32 s8, s8, 0xaaaaaaab
	s_lshr_b32 s85, s34, s85
	s_and_b32 s34, s90, s34
	s_bfe_u32 s56, s8, 0x30009
	s_lshl_b32 s34, s34, 5
	s_lshl_b32 s8, s8, 1
	s_and_b32 s91, s8, 0xfe000
	v_or_b32_e32 v184, s34, v162
	v_mov_b32_e32 v185, v167
	v_lshlrev_b64 v[64:65], s95, v[184:185]
	s_or_b32 s8, s85, s91
	s_add_i32 s96, s56, 1
	v_lshl_add_u64 v[190:191], v[64:65], 0, s[8:9]
	v_cvt_f32_ubyte0_e32 v64, s96
	v_exp_f32_e64 v185, -v64
	s_lshl_b32 s96, 1, s95
	v_lshlrev_b64 v[64:65], 12, v[190:191]
	v_cvt_f32_u32_e32 v204, s96
	v_lshl_add_u64 v[64:65], s[22:23], 0, v[64:65]
	s_lshl_b32 s96, s56, 7
	s_mov_b32 s97, s9
	v_lshl_add_u64 v[64:65], v[64:65], 0, s[96:97]
	v_mov_b32_e32 v177, v167
	v_lshl_add_u64 v[156:157], v[64:65], 0, v[176:177]
	v_lshlrev_b32_e32 v64, s95, v168
	v_add_u32_e32 v64, s8, v64
	v_mov_b32_e32 v65, v167
	s_and_b32 s90, s34, 0x1fc0
	v_lshlrev_b64 v[64:65], 12, v[64:65]
	v_lshl_add_u64 v[64:65], s[22:23], 0, v[64:65]
	s_cmp_eq_u32 s93, 1
	v_lshl_add_u64 v[64:65], v[64:65], 0, s[96:97]
	s_cselect_b32 s8, s20, s26
	s_cselect_b32 s96, s21, s27
	s_cmp_eq_u32 s93, 0
	s_cselect_b32 s96, s54, s96
	s_cselect_b32 s8, s49, s8
	v_lshl_or_b32 v66, s56, 6, v164
	v_lshl_add_u64 v[112:113], v[64:65], 0, v[178:179]
	v_lshl_add_u64 v[120:121], v[64:65], 0, v[180:181]
	v_mov_b32_e32 v64, s8
	v_mov_b32_e32 v65, s96
	v_mul_i32_i24_e32 v66, 0x18000, v66
	v_mov_b32_e32 v67, v167
	v_lshl_add_u64 v[64:65], v[66:67], 1, v[64:65]
	s_lshl_b32 s8, s91, 1
	v_lshl_add_u64 v[64:65], v[64:65], 0, s[8:9]
	s_sub_i32 s8, 13, s95
	s_lshl_b32 s8, s85, s8
	s_mov_b32 s91, s9
	s_lshl_b32 s8, s8, 1
	s_lshl_b64 s[96:97], s[90:91], s95
	v_lshl_add_u64 v[64:65], v[64:65], 0, s[8:9]
	s_lshl_b64 s[96:97], s[96:97], 12
	v_lshl_add_u64 v[196:197], v[64:65], 0, v[178:179]
	v_lshl_add_u64 v[198:199], v[64:65], 0, v[180:181]
	v_lshl_add_u64 v[64:65], v[112:113], 0, s[96:97]
	s_lshl_b32 s8, s90, 1
	s_or_b32 s96, s90, 4
	s_mov_b32 s97, s9
	s_lshl_b64 s[96:97], s[96:97], s95
	v_lshl_add_u64 v[140:141], v[198:199], 0, s[8:9]
	v_lshl_add_u64 v[116:117], v[196:197], 0, s[8:9]
	s_lshl_b64 s[96:97], s[96:97], 12
	v_add_co_u32_e32 v76, vcc, s1, v140
	s_or_b32 s8, s90, 16
	v_lshl_add_u64 v[72:73], v[120:121], 0, s[96:97]
	v_addc_co_u32_e32 v77, vcc, 0, v141, vcc
	s_lshl_b64 s[96:97], s[8:9], s95
	s_lshl_b64 s[96:97], s[96:97], 12
	v_add_co_u32_e32 v84, vcc, s52, v116
	s_or_b32 s8, s90, 20
	v_lshl_add_u64 v[80:81], v[112:113], 0, s[96:97]
	v_addc_co_u32_e32 v85, vcc, 0, v117, vcc
	s_lshl_b64 s[96:97], s[8:9], s95
	s_lshl_b64 s[96:97], s[96:97], 12
	v_add_co_u32_e32 v92, vcc, s53, v140
	s_or_b32 s8, s34, 32
	v_lshl_add_u64 v[88:89], v[120:121], 0, s[96:97]
	v_addc_co_u32_e32 v93, vcc, 0, v141, vcc
	s_lshl_b64 s[96:97], s[8:9], s95
	s_lshl_b64 s[96:97], s[96:97], 12
	v_add_co_u32_e32 v100, vcc, s6, v116
	s_or_b32 s8, s34, 36
	v_lshl_add_u64 v[96:97], v[112:113], 0, s[96:97]
	v_addc_co_u32_e32 v101, vcc, 0, v117, vcc
	s_lshl_b64 s[96:97], s[8:9], s95
	s_lshl_b64 s[96:97], s[96:97], 12
	v_add_co_u32_e32 v108, vcc, s7, v140
	s_or_b32 s8, s34, 48
	v_lshl_add_u64 v[104:105], v[120:121], 0, s[96:97]
	v_addc_co_u32_e32 v109, vcc, 0, v141, vcc
	s_lshl_b64 s[96:97], s[8:9], s95
	global_load_dwordx4 v[68:71], v[116:117], off
	s_lshl_b64 s[96:97], s[96:97], 12
	v_add_co_u32_e32 v116, vcc, s42, v116
	s_or_b32 s8, s34, 52
	v_lshl_add_u64 v[192:193], v[112:113], 0, s[10:11]
	v_lshl_add_u64 v[112:113], v[112:113], 0, s[96:97]
	v_addc_co_u32_e32 v117, vcc, 0, v117, vcc
	s_lshl_b64 s[96:97], s[8:9], s95
	s_lshl_b64 s[96:97], s[96:97], 12
	v_add_co_u32_e32 v140, vcc, 0xa80000, v140
	v_lshl_add_u64 v[194:195], v[120:121], 0, s[10:11]
	v_lshl_add_u64 v[120:121], v[120:121], 0, s[96:97]
	v_addc_co_u32_e32 v141, vcc, 0, v141, vcc
	global_load_dwordx4 v[64:67], v[64:65], off offset:3072
	v_mul_f32_e32 v177, 0x3fb8aa3b, v185
	global_load_dwordx4 v[72:75], v[72:73], off offset:3072
	s_lshr_b32 s34, 0x2000, s95
	global_load_dwordx4 v[76:79], v[76:77], off
	v_mul_f32_e32 v177, v177, v204
	global_load_dwordx4 v[80:83], v[80:81], off offset:3072
	s_nop 0
	global_load_dwordx4 v[84:87], v[84:85], off
	s_nop 0
	global_load_dwordx4 v[88:91], v[88:89], off offset:3072
	s_nop 0
	global_load_dwordx4 v[92:95], v[92:93], off
	s_nop 0
	global_load_dwordx4 v[96:99], v[96:97], off offset:3072
	s_nop 0
	global_load_dwordx4 v[100:103], v[100:101], off
	s_nop 0
	global_load_dwordx4 v[104:107], v[104:105], off offset:3072
	s_nop 0
	global_load_dwordx4 v[108:111], v[108:109], off
	s_nop 0
	global_load_dwordx4 v[112:115], v[112:113], off offset:3072
	s_nop 0
	global_load_dwordx4 v[116:119], v[116:117], off
	s_nop 0
	global_load_dwordx4 v[120:123], v[120:121], off offset:3072
	s_nop 0
	global_load_dwordx4 v[140:143], v[140:141], off
	s_nop 0
	global_load_dwordx4 v[144:147], v[156:157], off offset:2048
	global_load_dwordx4 v[148:151], v[156:157], off offset:2080
	global_load_dwordx4 v[152:155], v[156:157], off offset:2112
	s_nop 0
	global_load_dwordx4 v[156:159], v[156:157], off offset:2144

.LBB0_514:
	v_add_u32_e32 v32, 64, v208
	v_cvt_f32_i32_e32 v63, v32
	ds_read_b128 v[200:203], v223
	ds_read_b128 v[204:207], v223 offset:4096
	ds_read_b128 v[238:241], v224
	ds_read_b128 v[242:245], v224 offset:4096
	v_add_f32_e32 v33, 0xc2000000, v63
	v_fma_f32 v32, -v186, |v63|, -v188
	v_cmp_ngt_f32_e64 vcc, |v63|, s50
	v_fma_f32 v34, -v186, |v33|, -v188
	v_add_f32_e32 v62, 0xc2580000, v63
	v_cndmask_b32_e32 v32, v227, v32, vcc
	v_cmp_ngt_f32_e64 vcc, |v33|, s50
	v_add_f32_e32 v33, -1.0, v63
	v_fma_f32 v35, -v186, |v33|, -v188
	v_cndmask_b32_e32 v48, v227, v34, vcc
	v_add_f32_e32 v34, 0xc2040000, v63
	v_cmp_ngt_f32_e64 vcc, |v33|, s50
	v_fma_f32 v36, -v186, |v34|, -v188
	s_nop 0
	v_cndmask_b32_e32 v33, v227, v35, vcc
	v_cmp_ngt_f32_e64 vcc, |v34|, s50
	v_add_f32_e32 v34, -2.0, v63
	v_add_f32_e32 v35, 0xc2080000, v63
	v_cndmask_b32_e32 v49, v227, v36, vcc
	v_fma_f32 v36, -v186, |v34|, -v188
	v_cmp_ngt_f32_e64 vcc, |v34|, s50
	v_fma_f32 v37, -v186, |v35|, -v188
	s_nop 0
	v_cndmask_b32_e32 v34, v227, v36, vcc
	v_cmp_ngt_f32_e64 vcc, |v35|, s50
	v_add_f32_e32 v35, 0xc0400000, v63
	v_add_f32_e32 v36, 0xc20c0000, v63
	v_cndmask_b32_e32 v50, v227, v37, vcc
	v_fma_f32 v37, -v186, |v35|, -v188
	v_cmp_ngt_f32_e64 vcc, |v35|, s50
	v_fma_f32 v38, -v186, |v36|, -v188
	s_nop 0
	v_cndmask_b32_e32 v35, v227, v37, vcc
	v_cmp_ngt_f32_e64 vcc, |v36|, s50
	v_add_f32_e32 v36, -4.0, v63
	v_add_f32_e32 v37, 0xc2100000, v63
	v_cndmask_b32_e32 v51, v227, v38, vcc
	v_fma_f32 v38, -v186, |v36|, -v188
	v_cmp_ngt_f32_e64 vcc, |v36|, s50
	v_fma_f32 v39, -v186, |v37|, -v188
	s_nop 0
	v_cndmask_b32_e32 v36, v227, v38, vcc
	v_cmp_ngt_f32_e64 vcc, |v37|, s50
	v_add_f32_e32 v37, 0xc0a00000, v63
	v_add_f32_e32 v38, 0xc2140000, v63
	v_cndmask_b32_e32 v52, v227, v39, vcc
	v_fma_f32 v39, -v186, |v37|, -v188
	v_cmp_ngt_f32_e64 vcc, |v37|, s50
	v_fma_f32 v40, -v186, |v38|, -v188
	s_nop 0
	v_cndmask_b32_e32 v37, v227, v39, vcc
	v_cmp_ngt_f32_e64 vcc, |v38|, s50
	v_add_f32_e32 v38, 0xc0c00000, v63
	v_add_f32_e32 v39, 0xc2180000, v63
	v_cndmask_b32_e32 v53, v227, v40, vcc
	v_fma_f32 v40, -v186, |v38|, -v188
	v_cmp_ngt_f32_e64 vcc, |v38|, s50
	v_fma_f32 v41, -v186, |v39|, -v188
	s_nop 0
	v_cndmask_b32_e32 v38, v227, v40, vcc
	v_cmp_ngt_f32_e64 vcc, |v39|, s50
	v_add_f32_e32 v39, 0xc0e00000, v63
	v_add_f32_e32 v40, 0xc21c0000, v63
	v_cndmask_b32_e32 v54, v227, v41, vcc
	v_fma_f32 v41, -v186, |v39|, -v188
	v_cmp_ngt_f32_e64 vcc, |v39|, s50
	v_fma_f32 v42, -v186, |v40|, -v188
	s_nop 0
	v_cndmask_b32_e32 v39, v227, v41, vcc
	v_cmp_ngt_f32_e64 vcc, |v40|, s50
	v_add_f32_e32 v40, 0xc1800000, v63
	v_add_f32_e32 v41, 0xc2400000, v63
	v_cndmask_b32_e32 v55, v227, v42, vcc
	v_fma_f32 v42, -v186, |v40|, -v188
	v_cmp_ngt_f32_e64 vcc, |v40|, s50
	v_fma_f32 v43, -v186, |v41|, -v188
	s_nop 0
	v_cndmask_b32_e32 v40, v227, v42, vcc
	v_cmp_ngt_f32_e64 vcc, |v41|, s50
	v_add_f32_e32 v41, 0xc1880000, v63
	v_add_f32_e32 v42, 0xc2440000, v63
	v_cndmask_b32_e32 v56, v227, v43, vcc
	v_fma_f32 v43, -v186, |v41|, -v188
	v_cmp_ngt_f32_e64 vcc, |v41|, s50
	v_fma_f32 v44, -v186, |v42|, -v188
	s_nop 0
	v_cndmask_b32_e32 v41, v227, v43, vcc
	v_cmp_ngt_f32_e64 vcc, |v42|, s50
	v_add_f32_e32 v42, 0xc1900000, v63
	v_add_f32_e32 v43, 0xc2480000, v63
	v_cndmask_b32_e32 v57, v227, v44, vcc
	v_fma_f32 v44, -v186, |v42|, -v188
	v_cmp_ngt_f32_e64 vcc, |v42|, s50
	v_fma_f32 v45, -v186, |v43|, -v188
	s_nop 0
	v_cndmask_b32_e32 v42, v227, v44, vcc
	v_cmp_ngt_f32_e64 vcc, |v43|, s50
	v_add_f32_e32 v43, 0xc1980000, v63
	v_add_f32_e32 v44, 0xc24c0000, v63
	v_cndmask_b32_e32 v58, v227, v45, vcc
	v_fma_f32 v45, -v186, |v43|, -v188
	v_cmp_ngt_f32_e64 vcc, |v43|, s50
	v_fma_f32 v46, -v186, |v44|, -v188
	s_nop 0
	v_cndmask_b32_e32 v43, v227, v45, vcc
	v_cmp_ngt_f32_e64 vcc, |v44|, s50
	v_add_f32_e32 v44, 0xc1a00000, v63
	v_add_f32_e32 v45, 0xc2500000, v63
	v_cndmask_b32_e32 v59, v227, v46, vcc
	v_fma_f32 v46, -v186, |v44|, -v188
	v_cmp_ngt_f32_e64 vcc, |v44|, s50
	v_fma_f32 v47, -v186, |v45|, -v188
	s_nop 0
	v_cndmask_b32_e32 v44, v227, v46, vcc
	v_cmp_ngt_f32_e64 vcc, |v45|, s50
	v_add_f32_e32 v45, 0xc1a80000, v63
	v_add_f32_e32 v46, 0xc2540000, v63
	v_cndmask_b32_e32 v60, v227, v47, vcc
	v_fma_f32 v47, -v186, |v45|, -v188
	v_cmp_ngt_f32_e64 vcc, |v45|, s50
	v_fma_f32 v61, -v186, |v46|, -v188
	s_nop 0
	v_cndmask_b32_e32 v45, v227, v47, vcc
	v_cmp_ngt_f32_e64 vcc, |v46|, s50
	v_add_f32_e32 v46, 0xc1b00000, v63
	v_fma_f32 v47, -v186, |v46|, -v188
	v_cndmask_b32_e32 v61, v227, v61, vcc
	v_cmp_ngt_f32_e64 vcc, |v46|, s50
	s_nop 1
	v_cndmask_b32_e32 v46, v227, v47, vcc
	v_add_f32_e32 v47, 0xc1b80000, v63
	v_fma_f32 v185, -v186, |v47|, -v188
	v_cmp_ngt_f32_e64 vcc, |v47|, s50
	v_add_f32_e32 v63, 0xc25c0000, v63
	s_nop 0
	v_cndmask_b32_e32 v47, v227, v185, vcc
	v_fma_f32 v185, -v186, |v62|, -v188
	v_cmp_ngt_f32_e64 vcc, |v62|, s50
	s_waitcnt lgkmcnt(3)
	v_mfma_f32_32x32x16_bf16 v[32:47], v[200:203], v[136:139], v[32:47]
	v_cndmask_b32_e32 v62, v227, v185, vcc
	v_fma_f32 v185, -v186, |v63|, -v188
	v_cmp_ngt_f32_e64 vcc, |v63|, s50
	s_nop 1
	v_cndmask_b32_e32 v63, v227, v185, vcc
	s_waitcnt lgkmcnt(2)
	s_nop 0
	v_mfma_f32_32x32x16_bf16 v[48:63], v[204:207], v[136:139], v[48:63]
	ds_read_b128 v[200:203], v225
	ds_read_b128 v[204:207], v225 offset:4096
	s_waitcnt lgkmcnt(3)
	v_mfma_f32_32x32x16_bf16 v[32:47], v[238:241], v[132:135], v[32:47]
	s_waitcnt lgkmcnt(2)
	v_mfma_f32_32x32x16_bf16 v[48:63], v[242:245], v[132:135], v[48:63]
	ds_read_b128 v[238:241], v226
	ds_read_b128 v[242:245], v226 offset:4096
	s_waitcnt lgkmcnt(3)
	v_mfma_f32_32x32x16_bf16 v[32:47], v[200:203], v[128:131], v[32:47]
	s_waitcnt lgkmcnt(2)
	v_mfma_f32_32x32x16_bf16 v[48:63], v[204:207], v[128:131], v[48:63]
	s_waitcnt lgkmcnt(1)
	v_mfma_f32_32x32x16_bf16 v[32:47], v[238:241], v[124:127], v[32:47]
	s_waitcnt lgkmcnt(0)
	v_mfma_f32_32x32x16_bf16 v[48:63], v[242:245], v[124:127], v[48:63]
	s_nop 9
	v_max_f32_e32 v185, v33, v49
	v_max_f32_e32 v200, v34, v50
	v_max3_f32 v185, v32, v48, v185
	v_max_f32_e32 v201, v35, v51
	v_max3_f32 v185, v185, v200, v201
	v_max_f32_e32 v200, v36, v52
	v_max_f32_e32 v201, v37, v53
	v_max3_f32 v185, v185, v200, v201
	v_max_f32_e32 v200, v38, v54
	v_max_f32_e32 v201, v39, v55
	v_max3_f32 v185, v185, v200, v201
	v_max_f32_e32 v200, v40, v56
	v_max_f32_e32 v201, v41, v57
	v_max3_f32 v185, v185, v200, v201
	v_max_f32_e32 v200, v42, v58
	v_max_f32_e32 v201, v43, v59
	v_max3_f32 v185, v185, v200, v201
	v_max_f32_e32 v200, v44, v60
	v_max_f32_e32 v201, v45, v61
	v_max3_f32 v185, v185, v200, v201
	v_max_f32_e32 v200, v46, v62
	v_max_f32_e32 v201, v47, v63
	v_max3_f32 v185, v185, v200, v201
	v_mov_b32_e32 v200, v185
	s_nop 1
	v_permlane32_swap_b32 v185, v200
	s_nop 1
	s_nop 0
	v_max_f32_e32 v200, v200, v200
	v_max_f32_e32 v185, v185, v185
	v_max_f32_e32 v185, v185, v200
	v_cmp_lt_f32_e32 vcc, s51, v185
	s_cbranch_vccz .LBB0_516
	v_max_f32_e32 v185, v185, v185
	v_max_f32_e32 v200, 0, v185
	v_exp_f32_e64 v202, -v200
	v_add_f32_e32 v188, v188, v200
	v_pk_add_f32 v[32:33], v[32:33], v[200:201] op_sel_hi:[1,0] neg_lo:[0,1] neg_hi:[0,1]
	v_pk_add_f32 v[48:49], v[48:49], v[200:201] op_sel_hi:[1,0] neg_lo:[0,1] neg_hi:[0,1]
	v_pk_add_f32 v[34:35], v[34:35], v[200:201] op_sel_hi:[1,0] neg_lo:[0,1] neg_hi:[0,1]
	v_pk_add_f32 v[50:51], v[50:51], v[200:201] op_sel_hi:[1,0] neg_lo:[0,1] neg_hi:[0,1]
	v_pk_add_f32 v[36:37], v[36:37], v[200:201] op_sel_hi:[1,0] neg_lo:[0,1] neg_hi:[0,1]
	v_pk_add_f32 v[52:53], v[52:53], v[200:201] op_sel_hi:[1,0] neg_lo:[0,1] neg_hi:[0,1]
	v_pk_add_f32 v[38:39], v[38:39], v[200:201] op_sel_hi:[1,0] neg_lo:[0,1] neg_hi:[0,1]
	v_pk_add_f32 v[54:55], v[54:55], v[200:201] op_sel_hi:[1,0] neg_lo:[0,1] neg_hi:[0,1]
	v_pk_add_f32 v[40:41], v[40:41], v[200:201] op_sel_hi:[1,0] neg_lo:[0,1] neg_hi:[0,1]
	v_pk_add_f32 v[56:57], v[56:57], v[200:201] op_sel_hi:[1,0] neg_lo:[0,1] neg_hi:[0,1]
	v_pk_add_f32 v[42:43], v[42:43], v[200:201] op_sel_hi:[1,0] neg_lo:[0,1] neg_hi:[0,1]
	v_pk_add_f32 v[58:59], v[58:59], v[200:201] op_sel_hi:[1,0] neg_lo:[0,1] neg_hi:[0,1]
	v_pk_add_f32 v[44:45], v[44:45], v[200:201] op_sel_hi:[1,0] neg_lo:[0,1] neg_hi:[0,1]
	v_pk_add_f32 v[60:61], v[60:61], v[200:201] op_sel_hi:[1,0] neg_lo:[0,1] neg_hi:[0,1]
	v_pk_add_f32 v[46:47], v[46:47], v[200:201] op_sel_hi:[1,0] neg_lo:[0,1] neg_hi:[0,1]
	v_pk_add_f32 v[62:63], v[62:63], v[200:201] op_sel_hi:[1,0] neg_lo:[0,1] neg_hi:[0,1]
	v_mul_f32_e32 v189, v189, v202
	v_pk_mul_f32 v[30:31], v[30:31], v[202:203] op_sel_hi:[1,0]
	v_pk_mul_f32 v[28:29], v[28:29], v[202:203] op_sel_hi:[1,0]
	v_pk_mul_f32 v[26:27], v[26:27], v[202:203] op_sel_hi:[1,0]
	v_pk_mul_f32 v[24:25], v[24:25], v[202:203] op_sel_hi:[1,0]
	v_pk_mul_f32 v[22:23], v[22:23], v[202:203] op_sel_hi:[1,0]
	v_pk_mul_f32 v[20:21], v[20:21], v[202:203] op_sel_hi:[1,0]
	v_pk_mul_f32 v[18:19], v[18:19], v[202:203] op_sel_hi:[1,0]
	v_pk_mul_f32 v[16:17], v[16:17], v[202:203] op_sel_hi:[1,0]
	v_pk_mul_f32 v[14:15], v[14:15], v[202:203] op_sel_hi:[1,0]
	v_pk_mul_f32 v[12:13], v[12:13], v[202:203] op_sel_hi:[1,0]
	v_pk_mul_f32 v[10:11], v[10:11], v[202:203] op_sel_hi:[1,0]
	v_pk_mul_f32 v[8:9], v[8:9], v[202:203] op_sel_hi:[1,0]
	v_pk_mul_f32 v[6:7], v[6:7], v[202:203] op_sel_hi:[1,0]
	v_pk_mul_f32 v[4:5], v[4:5], v[202:203] op_sel_hi:[1,0]
	v_pk_mul_f32 v[2:3], v[2:3], v[202:203] op_sel_hi:[1,0]
	v_pk_mul_f32 v[0:1], v[0:1], v[202:203] op_sel_hi:[1,0]

.LBB0_519:
	v_subrev_u32_e32 v32, s84, v228
	v_cvt_f32_i32_e32 v47, v32
	ds_read_b128 v[200:203], v223
	ds_read_b128 v[204:207], v223 offset:4096
	ds_read_b128 v[238:241], v224
	ds_read_b128 v[242:245], v224 offset:4096
	v_add_f32_e32 v33, 0xc2000000, v47
	v_fma_f32 v32, -v186, |v47|, -v188
	v_cmp_ngt_f32_e64 vcc, |v47|, s50
	v_fma_f32 v34, -v186, |v33|, -v188
	s_nop 0
	v_cndmask_b32_e32 v32, v227, v32, vcc
	v_cmp_ngt_f32_e64 vcc, |v33|, s50
	v_add_f32_e32 v33, -1.0, v47
	v_fma_f32 v35, -v186, |v33|, -v188
	v_cndmask_b32_e32 v48, v227, v34, vcc
	v_add_f32_e32 v34, 0xc2040000, v47
	v_cmp_ngt_f32_e64 vcc, |v33|, s50
	v_fma_f32 v36, -v186, |v34|, -v188
	s_nop 0
	v_cndmask_b32_e32 v33, v227, v35, vcc
	v_cmp_ngt_f32_e64 vcc, |v34|, s50
	v_add_f32_e32 v34, -2.0, v47
	v_add_f32_e32 v35, 0xc2080000, v47
	v_cndmask_b32_e32 v49, v227, v36, vcc
	v_fma_f32 v36, -v186, |v34|, -v188
	v_cmp_ngt_f32_e64 vcc, |v34|, s50
	v_fma_f32 v37, -v186, |v35|, -v188
	s_nop 0
	v_cndmask_b32_e32 v34, v227, v36, vcc
	v_cmp_ngt_f32_e64 vcc, |v35|, s50
	v_add_f32_e32 v35, 0xc0400000, v47
	v_add_f32_e32 v36, 0xc20c0000, v47
	v_cndmask_b32_e32 v50, v227, v37, vcc
	v_fma_f32 v37, -v186, |v35|, -v188
	v_cmp_ngt_f32_e64 vcc, |v35|, s50
	v_fma_f32 v38, -v186, |v36|, -v188
	s_nop 0
	v_cndmask_b32_e32 v35, v227, v37, vcc
	v_cmp_ngt_f32_e64 vcc, |v36|, s50
	v_add_f32_e32 v36, -4.0, v47
	v_add_f32_e32 v37, 0xc2100000, v47
	v_cndmask_b32_e32 v51, v227, v38, vcc
	v_fma_f32 v38, -v186, |v36|, -v188
	v_cmp_ngt_f32_e64 vcc, |v36|, s50
	v_fma_f32 v39, -v186, |v37|, -v188
	s_nop 0
	v_cndmask_b32_e32 v36, v227, v38, vcc
	v_cmp_ngt_f32_e64 vcc, |v37|, s50
	v_add_f32_e32 v37, 0xc0a00000, v47
	v_add_f32_e32 v38, 0xc2140000, v47
	v_cndmask_b32_e32 v52, v227, v39, vcc
	v_fma_f32 v39, -v186, |v37|, -v188
	v_cmp_ngt_f32_e64 vcc, |v37|, s50
	v_fma_f32 v40, -v186, |v38|, -v188
	s_nop 0
	v_cndmask_b32_e32 v37, v227, v39, vcc
	v_cmp_ngt_f32_e64 vcc, |v38|, s50
	v_add_f32_e32 v38, 0xc0c00000, v47
	v_add_f32_e32 v39, 0xc2180000, v47
	v_cndmask_b32_e32 v53, v227, v40, vcc
	v_fma_f32 v40, -v186, |v38|, -v188
	v_cmp_ngt_f32_e64 vcc, |v38|, s50
	v_fma_f32 v41, -v186, |v39|, -v188
	s_nop 0
	v_cndmask_b32_e32 v38, v227, v40, vcc
	v_cmp_ngt_f32_e64 vcc, |v39|, s50
	v_add_f32_e32 v39, 0xc0e00000, v47
	v_add_f32_e32 v40, 0xc21c0000, v47
	v_cndmask_b32_e32 v54, v227, v41, vcc
	v_fma_f32 v41, -v186, |v39|, -v188
	v_cmp_ngt_f32_e64 vcc, |v39|, s50
	v_fma_f32 v42, -v186, |v40|, -v188
	s_nop 0
	v_cndmask_b32_e32 v39, v227, v41, vcc
	v_cmp_ngt_f32_e64 vcc, |v40|, s50
	v_add_f32_e32 v40, 0xc1800000, v47
	v_add_f32_e32 v41, 0xc2400000, v47
	v_cndmask_b32_e32 v55, v227, v42, vcc
	v_fma_f32 v42, -v186, |v40|, -v188
	v_cmp_ngt_f32_e64 vcc, |v40|, s50
	v_fma_f32 v43, -v186, |v41|, -v188
	s_nop 0
	v_cndmask_b32_e32 v40, v227, v42, vcc
	v_cmp_ngt_f32_e64 vcc, |v41|, s50
	v_add_f32_e32 v41, 0xc1880000, v47
	v_add_f32_e32 v42, 0xc2440000, v47
	v_cndmask_b32_e32 v56, v227, v43, vcc
	v_fma_f32 v43, -v186, |v41|, -v188
	v_cmp_ngt_f32_e64 vcc, |v41|, s50
	v_fma_f32 v44, -v186, |v42|, -v188
	s_nop 0
	v_cndmask_b32_e32 v41, v227, v43, vcc
	v_cmp_ngt_f32_e64 vcc, |v42|, s50
	v_add_f32_e32 v42, 0xc1900000, v47
	v_add_f32_e32 v43, 0xc2480000, v47
	v_cndmask_b32_e32 v57, v227, v44, vcc
	v_fma_f32 v44, -v186, |v42|, -v188
	v_cmp_ngt_f32_e64 vcc, |v42|, s50
	v_fma_f32 v45, -v186, |v43|, -v188
	s_nop 0
	v_cndmask_b32_e32 v42, v227, v44, vcc
	v_cmp_ngt_f32_e64 vcc, |v43|, s50
	v_add_f32_e32 v43, 0xc1980000, v47
	v_add_f32_e32 v44, 0xc24c0000, v47
	v_cndmask_b32_e32 v58, v227, v45, vcc
	v_fma_f32 v45, -v186, |v43|, -v188
	v_cmp_ngt_f32_e64 vcc, |v43|, s50
	v_fma_f32 v46, -v186, |v44|, -v188
	s_nop 0
	v_cndmask_b32_e32 v43, v227, v45, vcc
	v_cmp_ngt_f32_e64 vcc, |v44|, s50
	v_add_f32_e32 v44, 0xc1a00000, v47
	v_add_f32_e32 v45, 0xc2500000, v47
	v_cndmask_b32_e32 v59, v227, v46, vcc
	v_fma_f32 v46, -v186, |v44|, -v188
	v_cmp_ngt_f32_e64 vcc, |v44|, s50
	v_fma_f32 v60, -v186, |v45|, -v188
	s_nop 0
	v_cndmask_b32_e32 v44, v227, v46, vcc
	v_cmp_ngt_f32_e64 vcc, |v45|, s50
	v_add_f32_e32 v45, 0xc1a80000, v47
	v_add_f32_e32 v46, 0xc2540000, v47
	v_cndmask_b32_e32 v60, v227, v60, vcc
	v_fma_f32 v61, -v186, |v45|, -v188
	v_cmp_ngt_f32_e64 vcc, |v45|, s50
	v_fma_f32 v62, -v186, |v46|, -v188
	s_nop 0
	v_cndmask_b32_e32 v45, v227, v61, vcc
	v_cmp_ngt_f32_e64 vcc, |v46|, s50
	v_add_f32_e32 v46, 0xc1b00000, v47
	v_fma_f32 v63, -v186, |v46|, -v188
	v_cndmask_b32_e32 v61, v227, v62, vcc
	v_add_f32_e32 v62, 0xc2580000, v47
	v_cmp_ngt_f32_e64 vcc, |v46|, s50
	v_fma_f32 v185, -v186, |v62|, -v188
	s_nop 0
	v_cndmask_b32_e32 v46, v227, v63, vcc
	v_cmp_ngt_f32_e64 vcc, |v62|, s50
	v_add_f32_e32 v63, 0xc1b80000, v47
	s_nop 0
	v_cndmask_b32_e32 v62, v227, v185, vcc
	v_add_f32_e32 v185, 0xc25c0000, v47
	v_fma_f32 v47, -v186, |v63|, -v188
	v_cmp_ngt_f32_e64 vcc, |v63|, s50
	v_fma_f32 v186, -v186, |v185|, -v188
	s_nop 0
	v_cndmask_b32_e32 v47, v227, v47, vcc
	v_cmp_ngt_f32_e64 vcc, |v185|, s50
	s_waitcnt lgkmcnt(3)
	v_mfma_f32_32x32x16_bf16 v[32:47], v[200:203], v[136:139], v[32:47]
	v_cndmask_b32_e32 v63, v227, v186, vcc
	s_waitcnt lgkmcnt(2)
	s_nop 0
	v_mfma_f32_32x32x16_bf16 v[48:63], v[204:207], v[136:139], v[48:63]
	ds_read_b128 v[200:203], v225
	ds_read_b128 v[204:207], v225 offset:4096
	s_waitcnt lgkmcnt(3)
	v_mfma_f32_32x32x16_bf16 v[32:47], v[238:241], v[132:135], v[32:47]
	s_waitcnt lgkmcnt(2)
	v_mfma_f32_32x32x16_bf16 v[48:63], v[242:245], v[132:135], v[48:63]
	ds_read_b128 v[238:241], v226
	ds_read_b128 v[242:245], v226 offset:4096
	s_waitcnt lgkmcnt(3)
	v_mfma_f32_32x32x16_bf16 v[32:47], v[200:203], v[128:131], v[32:47]
	s_waitcnt lgkmcnt(2)
	v_mfma_f32_32x32x16_bf16 v[48:63], v[204:207], v[128:131], v[48:63]
	s_waitcnt lgkmcnt(1)
	v_mfma_f32_32x32x16_bf16 v[32:47], v[238:241], v[124:127], v[32:47]
	s_waitcnt lgkmcnt(0)
	v_mfma_f32_32x32x16_bf16 v[48:63], v[242:245], v[124:127], v[48:63]
	s_nop 9
	v_max_f32_e32 v124, v33, v49
	v_max_f32_e32 v125, v34, v50
	v_max3_f32 v124, v32, v48, v124
	v_max_f32_e32 v126, v35, v51
	v_max3_f32 v124, v124, v125, v126
	v_max_f32_e32 v125, v36, v52
	v_max_f32_e32 v126, v37, v53
	v_max3_f32 v124, v124, v125, v126
	v_max_f32_e32 v125, v38, v54
	v_max_f32_e32 v126, v39, v55
	v_max3_f32 v124, v124, v125, v126
	v_max_f32_e32 v125, v40, v56
	v_max_f32_e32 v126, v41, v57
	v_max3_f32 v124, v124, v125, v126
	v_max_f32_e32 v125, v42, v58
	v_max_f32_e32 v126, v43, v59
	v_max3_f32 v124, v124, v125, v126
	v_max_f32_e32 v125, v44, v60
	v_max_f32_e32 v126, v45, v61
	v_max3_f32 v124, v124, v125, v126
	v_max_f32_e32 v125, v46, v62
	v_max_f32_e32 v126, v47, v63
	v_max3_f32 v124, v124, v125, v126
	v_mov_b32_e32 v125, v124
	s_nop 1
	v_permlane32_swap_b32 v125, v124
	s_nop 1
	s_nop 0
	v_max_f32_e32 v124, v124, v124
	v_max_f32_e32 v125, v125, v125
	v_max_f32_e32 v124, v125, v124
	v_cmp_lt_f32_e32 vcc, s51, v124
	s_cbranch_vccz .LBB0_521
	v_max_f32_e32 v124, v124, v124
	v_max_f32_e32 v124, 0, v124
	v_exp_f32_e64 v126, -v124
	v_add_f32_e32 v188, v188, v124
	v_pk_add_f32 v[32:33], v[32:33], v[124:125] op_sel_hi:[1,0] neg_lo:[0,1] neg_hi:[0,1]
	v_pk_add_f32 v[48:49], v[48:49], v[124:125] op_sel_hi:[1,0] neg_lo:[0,1] neg_hi:[0,1]
	v_pk_add_f32 v[34:35], v[34:35], v[124:125] op_sel_hi:[1,0] neg_lo:[0,1] neg_hi:[0,1]
	v_pk_add_f32 v[50:51], v[50:51], v[124:125] op_sel_hi:[1,0] neg_lo:[0,1] neg_hi:[0,1]
	v_pk_add_f32 v[36:37], v[36:37], v[124:125] op_sel_hi:[1,0] neg_lo:[0,1] neg_hi:[0,1]
	v_pk_add_f32 v[52:53], v[52:53], v[124:125] op_sel_hi:[1,0] neg_lo:[0,1] neg_hi:[0,1]
	v_pk_add_f32 v[38:39], v[38:39], v[124:125] op_sel_hi:[1,0] neg_lo:[0,1] neg_hi:[0,1]
	v_pk_add_f32 v[54:55], v[54:55], v[124:125] op_sel_hi:[1,0] neg_lo:[0,1] neg_hi:[0,1]
	v_pk_add_f32 v[40:41], v[40:41], v[124:125] op_sel_hi:[1,0] neg_lo:[0,1] neg_hi:[0,1]
	v_pk_add_f32 v[56:57], v[56:57], v[124:125] op_sel_hi:[1,0] neg_lo:[0,1] neg_hi:[0,1]
	v_pk_add_f32 v[42:43], v[42:43], v[124:125] op_sel_hi:[1,0] neg_lo:[0,1] neg_hi:[0,1]
	v_pk_add_f32 v[58:59], v[58:59], v[124:125] op_sel_hi:[1,0] neg_lo:[0,1] neg_hi:[0,1]
	v_pk_add_f32 v[44:45], v[44:45], v[124:125] op_sel_hi:[1,0] neg_lo:[0,1] neg_hi:[0,1]
	v_pk_add_f32 v[60:61], v[60:61], v[124:125] op_sel_hi:[1,0] neg_lo:[0,1] neg_hi:[0,1]
	v_pk_add_f32 v[46:47], v[46:47], v[124:125] op_sel_hi:[1,0] neg_lo:[0,1] neg_hi:[0,1]
	v_pk_add_f32 v[62:63], v[62:63], v[124:125] op_sel_hi:[1,0] neg_lo:[0,1] neg_hi:[0,1]
	v_mul_f32_e32 v189, v189, v126
	v_pk_mul_f32 v[30:31], v[30:31], v[126:127] op_sel_hi:[1,0]
	v_pk_mul_f32 v[28:29], v[28:29], v[126:127] op_sel_hi:[1,0]
	v_pk_mul_f32 v[26:27], v[26:27], v[126:127] op_sel_hi:[1,0]
	v_pk_mul_f32 v[24:25], v[24:25], v[126:127] op_sel_hi:[1,0]
	v_pk_mul_f32 v[22:23], v[22:23], v[126:127] op_sel_hi:[1,0]
	v_pk_mul_f32 v[20:21], v[20:21], v[126:127] op_sel_hi:[1,0]
	v_pk_mul_f32 v[18:19], v[18:19], v[126:127] op_sel_hi:[1,0]
	v_pk_mul_f32 v[16:17], v[16:17], v[126:127] op_sel_hi:[1,0]
	v_pk_mul_f32 v[14:15], v[14:15], v[126:127] op_sel_hi:[1,0]
	v_pk_mul_f32 v[12:13], v[12:13], v[126:127] op_sel_hi:[1,0]
	v_pk_mul_f32 v[10:11], v[10:11], v[126:127] op_sel_hi:[1,0]
	v_pk_mul_f32 v[8:9], v[8:9], v[126:127] op_sel_hi:[1,0]
	v_pk_mul_f32 v[6:7], v[6:7], v[126:127] op_sel_hi:[1,0]
	v_pk_mul_f32 v[4:5], v[4:5], v[126:127] op_sel_hi:[1,0]
	v_pk_mul_f32 v[2:3], v[2:3], v[126:127] op_sel_hi:[1,0]
	v_pk_mul_f32 v[0:1], v[0:1], v[126:127] op_sel_hi:[1,0]
